# lever 7: Proj epilogue rstd row-sum via v_permlane16_swap / v_permlane32_swap instead of two ds_bpermute round trips per block (on v52)
# speedup vs baseline: 1.0049x; 1.0049x over previous
.LBB0_256:
	v_lshl_add_u32 v148, s40, 8, v137
	v_ashrrev_i32_e32 v149, 31, v148
	v_lshlrev_b64 v[150:151], 6, v[148:149]
	v_lshl_add_u64 v[152:153], v[142:143], 0, v[150:151]
	global_load_dwordx4 v[196:199], v[152:153], off offset:1024
	global_load_dwordx4 v[200:203], v[152:153], off offset:2048
	global_load_dwordx4 v[204:207], v[152:153], off offset:3072
	v_add_co_u32_e32 v208, vcc, 0x2000, v152
	s_nop 1
	v_addc_co_u32_e32 v209, vcc, 0, v153, vcc
	global_load_dwordx4 v[234:237], v[208:209], off
	global_load_dwordx4 v[238:241], v[208:209], off offset:1024
	global_load_dwordx4 v[222:225], v[208:209], off offset:2048
	global_load_dwordx4 v[208:211], v[208:209], off offset:3072
	global_load_dwordx4 v[152:155], v[152:153], off
	s_cmp_eq_u32 s10, 3
	s_cselect_b64 s[24:25], -1, 0
	s_or_b64 vcc, s[8:9], s[24:25]
	s_cmp_lt_i32 s10, 3
	s_cselect_b64 s[24:25], -1, 0
	s_and_b64 s[24:25], s[24:25], s[14:15]
	s_waitcnt vmcnt(0)
	v_mov_b32_e32 v156, v153
	v_mov_b32_e32 v157, v154
	v_mov_b32_e32 v153, v155
	v_pk_add_f32 v[152:153], v[156:157], v[152:153]
	v_mov_b32_e32 v154, 0x3e38aa3b
	v_add_f32_e32 v152, v152, v153
	v_mov_b32_e32 v153, v152
	s_nop 1
	v_permlane16_swap_b32_e32 v152, v153
	v_cndmask_b32_e32 v174, 1.0, v154, vcc
	s_andn2_b64 vcc, exec, s[24:25]
	s_waitcnt lgkmcnt(0)
	v_add_f32_e32 v152, v152, v153
	v_mov_b32_e32 v153, v152
	s_nop 1
	v_permlane32_swap_b32_e32 v152, v153
	s_waitcnt lgkmcnt(0)
	v_add_f32_e32 v152, v152, v153
	v_fmamk_f32 v152, v152, 0x3a800000, v216
	v_cmp_gt_f32_e64 s[42:43], s29, v152
	v_mul_f32_e32 v153, 0x4b800000, v152
	s_nop 0
	v_cndmask_b32_e64 v152, v152, v153, s[42:43]
	v_rsq_f32_e32 v152, v152
	v_cndmask_b32_e64 v153, 0, 1, s[24:25]
	v_cmp_ne_u32_e64 s[40:41], 1, v153
	v_mul_f32_e32 v153, 0x45800000, v152
	v_cndmask_b32_e64 v152, v152, v153, s[42:43]
	v_mul_f32_e32 v152, v174, v152
	v_pk_mul_f32 v[126:127], v[126:127], v[152:153] op_sel_hi:[1,0]
	v_pk_mul_f32 v[124:125], v[124:125], v[152:153] op_sel_hi:[1,0]
	v_pk_mul_f32 v[122:123], v[122:123], v[152:153] op_sel_hi:[1,0]
	v_pk_mul_f32 v[120:121], v[120:121], v[152:153] op_sel_hi:[1,0]
	s_cbranch_vccnz .LBB0_260
	ds_bpermute_b32 v170, v169, v124
	ds_bpermute_b32 v156, v169, v120
	ds_bpermute_b32 v171, v169, v125
	ds_bpermute_b32 v157, v169, v121
	ds_bpermute_b32 v158, v169, v126
	ds_bpermute_b32 v154, v169, v122
	ds_bpermute_b32 v159, v169, v127
	ds_bpermute_b32 v155, v169, v123
	s_and_saveexec_b64 s[42:43], s[36:37]
	s_cbranch_execz .LBB0_259
	v_lshl_add_u64 v[162:163], s[20:21], 0, v[150:151]
	global_load_dwordx4 v[176:179], v[162:163], off
	global_load_dwordx4 v[180:183], v[162:163], off offset:32
	global_load_dwordx4 v[184:187], v[162:163], off offset:16
	global_load_dwordx4 v[188:191], v[162:163], off offset:48
	s_waitcnt vmcnt(3)
	v_pk_mul_f32 v[126:127], v[126:127], v[178:179]
	v_pk_mul_f32 v[124:125], v[124:125], v[176:177]
	s_waitcnt vmcnt(2) lgkmcnt(5)
	v_pk_mul_f32 v[162:163], v[180:181], v[170:171]
	s_waitcnt lgkmcnt(1)
	v_pk_mul_f32 v[158:159], v[182:183], v[158:159]
	s_waitcnt vmcnt(1)
	v_pk_mul_f32 v[122:123], v[122:123], v[186:187]
	v_pk_mul_f32 v[120:121], v[120:121], v[184:185]
	s_waitcnt vmcnt(0)
	v_pk_mul_f32 v[156:157], v[188:189], v[156:157]
	s_waitcnt lgkmcnt(0)
	v_pk_mul_f32 v[154:155], v[190:191], v[154:155]
	v_pk_fma_f32 v[126:127], v[140:141], v[158:159], v[126:127]
	v_pk_fma_f32 v[124:125], v[138:139], v[162:163], v[124:125]
	v_pk_fma_f32 v[122:123], v[140:141], v[154:155], v[122:123]
	v_pk_fma_f32 v[120:121], v[138:139], v[156:157], v[120:121]

.LBB0_264:
	v_cvt_pk_bf16_f32 v116, v116, v117
	v_cvt_pk_bf16_f32 v117, v118, v119
	v_cvt_pk_bf16_f32 v119, v114, v115
	v_or_b32_e32 v114, 16, v148
	v_ashrrev_i32_e32 v115, 31, v114
	v_cvt_pk_bf16_f32 v118, v112, v113
	v_lshlrev_b64 v[112:113], 6, v[114:115]
	global_store_dwordx4 v[120:121], v[116:119], off offset:256
	s_and_b64 vcc, exec, s[40:41]
	s_nop 0
	v_lshl_add_u64 v[116:117], v[142:143], 0, v[112:113]
	v_mov_b32_e32 v116, v196
	v_mov_b32_e32 v117, v197
	v_mov_b32_e32 v118, v198
	v_mov_b32_e32 v119, v199
	v_mov_b32_e32 v120, v117
	v_mov_b32_e32 v121, v118
	v_mov_b32_e32 v117, v119
	v_pk_add_f32 v[116:117], v[120:121], v[116:117]
	s_nop 0
	v_add_f32_e32 v116, v116, v117
	v_mov_b32_e32 v117, v116
	s_nop 1
	v_permlane16_swap_b32_e32 v116, v117
	s_waitcnt lgkmcnt(0)
	v_add_f32_e32 v116, v116, v117
	v_mov_b32_e32 v117, v116
	s_nop 1
	v_permlane32_swap_b32_e32 v116, v117
	s_waitcnt lgkmcnt(0)
	v_add_f32_e32 v116, v116, v117
	v_fmamk_f32 v116, v116, 0x3a800000, v216
	v_mul_f32_e32 v117, 0x4b800000, v116
	v_cmp_gt_f32_e64 s[42:43], s29, v116
	s_nop 1
	v_cndmask_b32_e64 v116, v116, v117, s[42:43]
	v_rsq_f32_e32 v116, v116
	s_nop 0
	v_mul_f32_e32 v117, 0x45800000, v116
	v_cndmask_b32_e64 v116, v116, v117, s[42:43]
	v_mul_f32_e32 v116, v174, v116
	v_pk_mul_f32 v[110:111], v[110:111], v[116:117] op_sel_hi:[1,0]
	v_pk_mul_f32 v[108:109], v[108:109], v[116:117] op_sel_hi:[1,0]
	v_pk_mul_f32 v[106:107], v[106:107], v[116:117] op_sel_hi:[1,0]
	v_pk_mul_f32 v[104:105], v[104:105], v[116:117] op_sel_hi:[1,0]
	s_cbranch_vccnz .LBB0_268
	ds_bpermute_b32 v124, v169, v108
	ds_bpermute_b32 v120, v169, v104
	ds_bpermute_b32 v125, v169, v109
	ds_bpermute_b32 v121, v169, v105
	ds_bpermute_b32 v122, v169, v110
	ds_bpermute_b32 v118, v169, v106
	ds_bpermute_b32 v123, v169, v111
	ds_bpermute_b32 v119, v169, v107
	s_and_saveexec_b64 s[42:43], s[36:37]
	s_cbranch_execz .LBB0_267
	v_lshl_add_u64 v[126:127], s[20:21], 0, v[112:113]
	global_load_dwordx4 v[150:153], v[126:127], off
	global_load_dwordx4 v[154:157], v[126:127], off offset:32
	global_load_dwordx4 v[176:179], v[126:127], off offset:16
	global_load_dwordx4 v[180:183], v[126:127], off offset:48
	s_waitcnt vmcnt(3)
	v_pk_mul_f32 v[110:111], v[110:111], v[152:153]
	v_pk_mul_f32 v[108:109], v[108:109], v[150:151]
	s_waitcnt vmcnt(2) lgkmcnt(5)
	v_pk_mul_f32 v[124:125], v[154:155], v[124:125]
	s_waitcnt lgkmcnt(1)
	v_pk_mul_f32 v[122:123], v[156:157], v[122:123]
	s_waitcnt vmcnt(1)
	v_pk_mul_f32 v[106:107], v[106:107], v[178:179]
	v_pk_mul_f32 v[104:105], v[104:105], v[176:177]
	s_waitcnt vmcnt(0)
	v_pk_mul_f32 v[120:121], v[180:181], v[120:121]
	s_waitcnt lgkmcnt(0)
	v_pk_mul_f32 v[118:119], v[182:183], v[118:119]
	v_pk_fma_f32 v[110:111], v[140:141], v[122:123], v[110:111]
	v_pk_fma_f32 v[108:109], v[138:139], v[124:125], v[108:109]
	v_pk_fma_f32 v[106:107], v[140:141], v[118:119], v[106:107]
	v_pk_fma_f32 v[104:105], v[138:139], v[120:121], v[104:105]

.LBB0_272:
	v_cvt_pk_bf16_f32 v100, v100, v101
	v_cvt_pk_bf16_f32 v101, v102, v103
	v_cvt_pk_bf16_f32 v103, v98, v99
	v_or_b32_e32 v98, 32, v148
	v_ashrrev_i32_e32 v99, 31, v98
	v_cvt_pk_bf16_f32 v102, v96, v97
	v_lshlrev_b64 v[96:97], 6, v[98:99]
	global_store_dwordx4 v[104:105], v[100:103], off offset:256
	s_and_b64 vcc, exec, s[40:41]
	s_nop 0
	v_lshl_add_u64 v[100:101], v[142:143], 0, v[96:97]
	v_mov_b32_e32 v100, v200
	v_mov_b32_e32 v101, v201
	v_mov_b32_e32 v102, v202
	v_mov_b32_e32 v103, v203
	v_mov_b32_e32 v104, v101
	v_mov_b32_e32 v105, v102
	v_mov_b32_e32 v101, v103
	v_pk_add_f32 v[100:101], v[104:105], v[100:101]
	s_nop 0
	v_add_f32_e32 v100, v100, v101
	v_mov_b32_e32 v101, v100
	s_nop 1
	v_permlane16_swap_b32_e32 v100, v101
	s_waitcnt lgkmcnt(0)
	v_add_f32_e32 v100, v100, v101
	v_mov_b32_e32 v101, v100
	s_nop 1
	v_permlane32_swap_b32_e32 v100, v101
	s_waitcnt lgkmcnt(0)
	v_add_f32_e32 v100, v100, v101
	v_fmamk_f32 v100, v100, 0x3a800000, v216
	v_mul_f32_e32 v101, 0x4b800000, v100
	v_cmp_gt_f32_e64 s[42:43], s29, v100
	s_nop 1
	v_cndmask_b32_e64 v100, v100, v101, s[42:43]
	v_rsq_f32_e32 v100, v100
	s_nop 0
	v_mul_f32_e32 v101, 0x45800000, v100
	v_cndmask_b32_e64 v100, v100, v101, s[42:43]
	v_mul_f32_e32 v100, v174, v100
	v_pk_mul_f32 v[94:95], v[94:95], v[100:101] op_sel_hi:[1,0]
	v_pk_mul_f32 v[92:93], v[92:93], v[100:101] op_sel_hi:[1,0]
	v_pk_mul_f32 v[90:91], v[90:91], v[100:101] op_sel_hi:[1,0]
	v_pk_mul_f32 v[88:89], v[88:89], v[100:101] op_sel_hi:[1,0]
	s_cbranch_vccnz .LBB0_276
	ds_bpermute_b32 v108, v169, v92
	ds_bpermute_b32 v104, v169, v88
	ds_bpermute_b32 v109, v169, v93
	ds_bpermute_b32 v105, v169, v89
	ds_bpermute_b32 v106, v169, v94
	ds_bpermute_b32 v102, v169, v90
	ds_bpermute_b32 v107, v169, v95
	ds_bpermute_b32 v103, v169, v91
	s_and_saveexec_b64 s[42:43], s[36:37]
	s_cbranch_execz .LBB0_275
	v_lshl_add_u64 v[122:123], s[20:21], 0, v[96:97]
	global_load_dwordx4 v[110:113], v[122:123], off
	global_load_dwordx4 v[114:117], v[122:123], off offset:32
	global_load_dwordx4 v[118:121], v[122:123], off offset:16
	s_nop 0
	global_load_dwordx4 v[122:125], v[122:123], off offset:48
	s_waitcnt vmcnt(3)
	v_pk_mul_f32 v[94:95], v[94:95], v[112:113]
	v_pk_mul_f32 v[92:93], v[92:93], v[110:111]
	s_waitcnt vmcnt(2) lgkmcnt(5)
	v_pk_mul_f32 v[108:109], v[114:115], v[108:109]
	s_waitcnt lgkmcnt(1)
	v_pk_mul_f32 v[106:107], v[116:117], v[106:107]
	s_waitcnt vmcnt(1)
	v_pk_mul_f32 v[90:91], v[90:91], v[120:121]
	v_pk_mul_f32 v[88:89], v[88:89], v[118:119]
	s_waitcnt vmcnt(0)
	v_pk_mul_f32 v[104:105], v[122:123], v[104:105]
	s_waitcnt lgkmcnt(0)
	v_pk_mul_f32 v[102:103], v[124:125], v[102:103]
	v_pk_fma_f32 v[94:95], v[140:141], v[106:107], v[94:95]
	v_pk_fma_f32 v[92:93], v[138:139], v[108:109], v[92:93]
	v_pk_fma_f32 v[90:91], v[140:141], v[102:103], v[90:91]
	v_pk_fma_f32 v[88:89], v[138:139], v[104:105], v[88:89]

.LBB0_280:
	v_cvt_pk_bf16_f32 v84, v84, v85
	v_cvt_pk_bf16_f32 v85, v86, v87
	v_cvt_pk_bf16_f32 v87, v82, v83
	v_or_b32_e32 v82, 48, v148
	v_ashrrev_i32_e32 v83, 31, v82
	v_cvt_pk_bf16_f32 v86, v80, v81
	v_lshlrev_b64 v[80:81], 6, v[82:83]
	global_store_dwordx4 v[88:89], v[84:87], off offset:256
	s_and_b64 vcc, exec, s[40:41]
	s_nop 0
	v_lshl_add_u64 v[84:85], v[142:143], 0, v[80:81]
	v_mov_b32_e32 v84, v204
	v_mov_b32_e32 v85, v205
	v_mov_b32_e32 v86, v206
	v_mov_b32_e32 v87, v207
	v_mov_b32_e32 v88, v85
	v_mov_b32_e32 v89, v86
	v_mov_b32_e32 v85, v87
	v_pk_add_f32 v[84:85], v[88:89], v[84:85]
	s_nop 0
	v_add_f32_e32 v84, v84, v85
	v_mov_b32_e32 v85, v84
	s_nop 1
	v_permlane16_swap_b32_e32 v84, v85
	s_waitcnt lgkmcnt(0)
	v_add_f32_e32 v84, v84, v85
	v_mov_b32_e32 v85, v84
	s_nop 1
	v_permlane32_swap_b32_e32 v84, v85
	s_waitcnt lgkmcnt(0)
	v_add_f32_e32 v84, v84, v85
	v_fmamk_f32 v84, v84, 0x3a800000, v216
	v_mul_f32_e32 v85, 0x4b800000, v84
	v_cmp_gt_f32_e64 s[42:43], s29, v84
	s_nop 1
	v_cndmask_b32_e64 v84, v84, v85, s[42:43]
	v_rsq_f32_e32 v84, v84
	s_nop 0
	v_mul_f32_e32 v85, 0x45800000, v84
	v_cndmask_b32_e64 v84, v84, v85, s[42:43]
	v_mul_f32_e32 v84, v174, v84
	v_pk_mul_f32 v[78:79], v[78:79], v[84:85] op_sel_hi:[1,0]
	v_pk_mul_f32 v[76:77], v[76:77], v[84:85] op_sel_hi:[1,0]
	v_pk_mul_f32 v[74:75], v[74:75], v[84:85] op_sel_hi:[1,0]
	v_pk_mul_f32 v[72:73], v[72:73], v[84:85] op_sel_hi:[1,0]
	s_cbranch_vccnz .LBB0_284
	ds_bpermute_b32 v92, v169, v76
	ds_bpermute_b32 v88, v169, v72
	ds_bpermute_b32 v93, v169, v77
	ds_bpermute_b32 v89, v169, v73
	ds_bpermute_b32 v90, v169, v78
	ds_bpermute_b32 v86, v169, v74
	ds_bpermute_b32 v91, v169, v79
	ds_bpermute_b32 v87, v169, v75
	s_and_saveexec_b64 s[42:43], s[36:37]
	s_cbranch_execz .LBB0_283
	v_lshl_add_u64 v[106:107], s[20:21], 0, v[80:81]
	global_load_dwordx4 v[94:97], v[106:107], off
	global_load_dwordx4 v[98:101], v[106:107], off offset:32
	global_load_dwordx4 v[102:105], v[106:107], off offset:16
	s_nop 0
	global_load_dwordx4 v[106:109], v[106:107], off offset:48
	s_waitcnt vmcnt(3)
	v_pk_mul_f32 v[78:79], v[78:79], v[96:97]
	v_pk_mul_f32 v[76:77], v[76:77], v[94:95]
	s_waitcnt vmcnt(2) lgkmcnt(5)
	v_pk_mul_f32 v[92:93], v[98:99], v[92:93]
	s_waitcnt lgkmcnt(1)
	v_pk_mul_f32 v[90:91], v[100:101], v[90:91]
	s_waitcnt vmcnt(1)
	v_pk_mul_f32 v[74:75], v[74:75], v[104:105]
	v_pk_mul_f32 v[72:73], v[72:73], v[102:103]
	s_waitcnt vmcnt(0)
	v_pk_mul_f32 v[88:89], v[106:107], v[88:89]
	s_waitcnt lgkmcnt(0)
	v_pk_mul_f32 v[86:87], v[108:109], v[86:87]
	v_pk_fma_f32 v[78:79], v[140:141], v[90:91], v[78:79]
	v_pk_fma_f32 v[76:77], v[138:139], v[92:93], v[76:77]
	v_pk_fma_f32 v[74:75], v[140:141], v[86:87], v[74:75]
	v_pk_fma_f32 v[72:73], v[138:139], v[88:89], v[72:73]

.LBB0_288:
	v_cvt_pk_bf16_f32 v68, v68, v69
	v_cvt_pk_bf16_f32 v69, v70, v71
	v_cvt_pk_bf16_f32 v71, v66, v67
	v_add_u32_e32 v66, 0x80, v148
	v_ashrrev_i32_e32 v67, 31, v66
	v_cvt_pk_bf16_f32 v70, v64, v65
	v_lshlrev_b64 v[64:65], 6, v[66:67]
	global_store_dwordx4 v[72:73], v[68:71], off offset:256
	s_and_b64 vcc, exec, s[40:41]
	s_nop 0
	v_lshl_add_u64 v[68:69], v[142:143], 0, v[64:65]
	v_mov_b32_e32 v68, v234
	v_mov_b32_e32 v69, v235
	v_mov_b32_e32 v70, v236
	v_mov_b32_e32 v71, v237
	v_mov_b32_e32 v72, v69
	v_mov_b32_e32 v73, v70
	v_mov_b32_e32 v69, v71
	v_pk_add_f32 v[68:69], v[72:73], v[68:69]
	s_nop 0
	v_add_f32_e32 v68, v68, v69
	v_mov_b32_e32 v69, v68
	s_nop 1
	v_permlane16_swap_b32_e32 v68, v69
	s_waitcnt lgkmcnt(0)
	v_add_f32_e32 v68, v68, v69
	v_mov_b32_e32 v69, v68
	s_nop 1
	v_permlane32_swap_b32_e32 v68, v69
	s_waitcnt lgkmcnt(0)
	v_add_f32_e32 v68, v68, v69
	v_fmamk_f32 v68, v68, 0x3a800000, v216
	v_mul_f32_e32 v69, 0x4b800000, v68
	v_cmp_gt_f32_e64 s[42:43], s29, v68
	s_nop 1
	v_cndmask_b32_e64 v68, v68, v69, s[42:43]
	v_rsq_f32_e32 v68, v68
	s_nop 0
	v_mul_f32_e32 v69, 0x45800000, v68
	v_cndmask_b32_e64 v68, v68, v69, s[42:43]
	v_mul_f32_e32 v68, v174, v68
	v_pk_mul_f32 v[62:63], v[62:63], v[68:69] op_sel_hi:[1,0]
	v_pk_mul_f32 v[60:61], v[60:61], v[68:69] op_sel_hi:[1,0]
	v_pk_mul_f32 v[58:59], v[58:59], v[68:69] op_sel_hi:[1,0]
	v_pk_mul_f32 v[56:57], v[56:57], v[68:69] op_sel_hi:[1,0]
	s_cbranch_vccnz .LBB0_292
	ds_bpermute_b32 v76, v169, v60
	ds_bpermute_b32 v72, v169, v56
	ds_bpermute_b32 v77, v169, v61
	ds_bpermute_b32 v73, v169, v57
	ds_bpermute_b32 v74, v169, v62
	ds_bpermute_b32 v70, v169, v58
	ds_bpermute_b32 v75, v169, v63
	ds_bpermute_b32 v71, v169, v59
	s_and_saveexec_b64 s[42:43], s[36:37]
	s_cbranch_execz .LBB0_291
	v_lshl_add_u64 v[90:91], s[20:21], 0, v[64:65]
	global_load_dwordx4 v[78:81], v[90:91], off
	global_load_dwordx4 v[82:85], v[90:91], off offset:32
	global_load_dwordx4 v[86:89], v[90:91], off offset:16
	s_nop 0
	global_load_dwordx4 v[90:93], v[90:91], off offset:48
	s_waitcnt vmcnt(3)
	v_pk_mul_f32 v[62:63], v[62:63], v[80:81]
	v_pk_mul_f32 v[60:61], v[60:61], v[78:79]
	s_waitcnt vmcnt(2) lgkmcnt(5)
	v_pk_mul_f32 v[76:77], v[82:83], v[76:77]
	s_waitcnt lgkmcnt(1)
	v_pk_mul_f32 v[74:75], v[84:85], v[74:75]
	s_waitcnt vmcnt(1)
	v_pk_mul_f32 v[58:59], v[58:59], v[88:89]
	v_pk_mul_f32 v[56:57], v[56:57], v[86:87]
	s_waitcnt vmcnt(0)
	v_pk_mul_f32 v[72:73], v[90:91], v[72:73]
	s_waitcnt lgkmcnt(0)
	v_pk_mul_f32 v[70:71], v[92:93], v[70:71]
	v_pk_fma_f32 v[62:63], v[140:141], v[74:75], v[62:63]
	v_pk_fma_f32 v[60:61], v[138:139], v[76:77], v[60:61]
	v_pk_fma_f32 v[58:59], v[140:141], v[70:71], v[58:59]
	v_pk_fma_f32 v[56:57], v[138:139], v[72:73], v[56:57]

.LBB0_296:
	v_cvt_pk_bf16_f32 v52, v52, v53
	v_cvt_pk_bf16_f32 v53, v54, v55
	v_cvt_pk_bf16_f32 v55, v50, v51
	v_add_u32_e32 v50, 0x90, v148
	v_ashrrev_i32_e32 v51, 31, v50
	v_cvt_pk_bf16_f32 v54, v48, v49
	v_lshlrev_b64 v[48:49], 6, v[50:51]
	global_store_dwordx4 v[56:57], v[52:55], off offset:256
	s_and_b64 vcc, exec, s[40:41]
	s_nop 0
	v_lshl_add_u64 v[52:53], v[142:143], 0, v[48:49]
	v_mov_b32_e32 v52, v238
	v_mov_b32_e32 v53, v239
	v_mov_b32_e32 v54, v240
	v_mov_b32_e32 v55, v241
	v_mov_b32_e32 v56, v53
	v_mov_b32_e32 v57, v54
	v_mov_b32_e32 v53, v55
	v_pk_add_f32 v[52:53], v[56:57], v[52:53]
	s_nop 0
	v_add_f32_e32 v52, v52, v53
	v_mov_b32_e32 v53, v52
	s_nop 1
	v_permlane16_swap_b32_e32 v52, v53
	s_waitcnt lgkmcnt(0)
	v_add_f32_e32 v52, v52, v53
	v_mov_b32_e32 v53, v52
	s_nop 1
	v_permlane32_swap_b32_e32 v52, v53
	s_waitcnt lgkmcnt(0)
	v_add_f32_e32 v52, v52, v53
	v_fmamk_f32 v52, v52, 0x3a800000, v216
	v_mul_f32_e32 v53, 0x4b800000, v52
	v_cmp_gt_f32_e64 s[42:43], s29, v52
	s_nop 1
	v_cndmask_b32_e64 v52, v52, v53, s[42:43]
	v_rsq_f32_e32 v52, v52
	s_nop 0
	v_mul_f32_e32 v53, 0x45800000, v52
	v_cndmask_b32_e64 v52, v52, v53, s[42:43]
	v_mul_f32_e32 v52, v174, v52
	v_pk_mul_f32 v[46:47], v[46:47], v[52:53] op_sel_hi:[1,0]
	v_pk_mul_f32 v[44:45], v[44:45], v[52:53] op_sel_hi:[1,0]
	v_pk_mul_f32 v[42:43], v[42:43], v[52:53] op_sel_hi:[1,0]
	v_pk_mul_f32 v[40:41], v[40:41], v[52:53] op_sel_hi:[1,0]
	s_cbranch_vccnz .LBB0_300
	ds_bpermute_b32 v60, v169, v44
	ds_bpermute_b32 v56, v169, v40
	ds_bpermute_b32 v61, v169, v45
	ds_bpermute_b32 v57, v169, v41
	ds_bpermute_b32 v58, v169, v46
	ds_bpermute_b32 v54, v169, v42
	ds_bpermute_b32 v59, v169, v47
	ds_bpermute_b32 v55, v169, v43
	s_and_saveexec_b64 s[42:43], s[36:37]
	s_cbranch_execz .LBB0_299
	v_lshl_add_u64 v[74:75], s[20:21], 0, v[48:49]
	global_load_dwordx4 v[62:65], v[74:75], off
	global_load_dwordx4 v[66:69], v[74:75], off offset:32
	global_load_dwordx4 v[70:73], v[74:75], off offset:16
	s_nop 0
	global_load_dwordx4 v[74:77], v[74:75], off offset:48
	s_waitcnt vmcnt(3)
	v_pk_mul_f32 v[46:47], v[46:47], v[64:65]
	v_pk_mul_f32 v[44:45], v[44:45], v[62:63]
	s_waitcnt vmcnt(2) lgkmcnt(5)
	v_pk_mul_f32 v[60:61], v[66:67], v[60:61]
	s_waitcnt lgkmcnt(1)
	v_pk_mul_f32 v[58:59], v[68:69], v[58:59]
	s_waitcnt vmcnt(1)
	v_pk_mul_f32 v[42:43], v[42:43], v[72:73]
	v_pk_mul_f32 v[40:41], v[40:41], v[70:71]
	s_waitcnt vmcnt(0)
	v_pk_mul_f32 v[56:57], v[74:75], v[56:57]
	s_waitcnt lgkmcnt(0)
	v_pk_mul_f32 v[54:55], v[76:77], v[54:55]
	v_pk_fma_f32 v[46:47], v[140:141], v[58:59], v[46:47]
	v_pk_fma_f32 v[44:45], v[138:139], v[60:61], v[44:45]
	v_pk_fma_f32 v[42:43], v[140:141], v[54:55], v[42:43]
	v_pk_fma_f32 v[40:41], v[138:139], v[56:57], v[40:41]

.LBB0_304:
	v_cvt_pk_bf16_f32 v36, v36, v37
	v_cvt_pk_bf16_f32 v37, v38, v39
	v_cvt_pk_bf16_f32 v39, v34, v35
	v_add_u32_e32 v34, 0xa0, v148
	v_ashrrev_i32_e32 v35, 31, v34
	v_cvt_pk_bf16_f32 v38, v32, v33
	v_lshlrev_b64 v[32:33], 6, v[34:35]
	global_store_dwordx4 v[40:41], v[36:39], off offset:256
	s_and_b64 vcc, exec, s[40:41]
	s_nop 0
	v_lshl_add_u64 v[36:37], v[142:143], 0, v[32:33]
	v_mov_b32_e32 v36, v222
	v_mov_b32_e32 v37, v223
	v_mov_b32_e32 v38, v224
	v_mov_b32_e32 v39, v225
	v_mov_b32_e32 v40, v37
	v_mov_b32_e32 v41, v38
	v_mov_b32_e32 v37, v39
	v_pk_add_f32 v[36:37], v[40:41], v[36:37]
	s_nop 0
	v_add_f32_e32 v36, v36, v37
	v_mov_b32_e32 v37, v36
	s_nop 1
	v_permlane16_swap_b32_e32 v36, v37
	s_waitcnt lgkmcnt(0)
	v_add_f32_e32 v36, v36, v37
	v_mov_b32_e32 v37, v36
	s_nop 1
	v_permlane32_swap_b32_e32 v36, v37
	s_waitcnt lgkmcnt(0)
	v_add_f32_e32 v36, v36, v37
	v_fmamk_f32 v36, v36, 0x3a800000, v216
	v_mul_f32_e32 v37, 0x4b800000, v36
	v_cmp_gt_f32_e64 s[42:43], s29, v36
	s_nop 1
	v_cndmask_b32_e64 v36, v36, v37, s[42:43]
	v_rsq_f32_e32 v36, v36
	s_nop 0
	v_mul_f32_e32 v37, 0x45800000, v36
	v_cndmask_b32_e64 v36, v36, v37, s[42:43]
	v_mul_f32_e32 v36, v174, v36
	v_pk_mul_f32 v[30:31], v[30:31], v[36:37] op_sel_hi:[1,0]
	v_pk_mul_f32 v[28:29], v[28:29], v[36:37] op_sel_hi:[1,0]
	v_pk_mul_f32 v[26:27], v[26:27], v[36:37] op_sel_hi:[1,0]
	v_pk_mul_f32 v[24:25], v[24:25], v[36:37] op_sel_hi:[1,0]
	s_cbranch_vccnz .LBB0_308
	ds_bpermute_b32 v44, v169, v28
	ds_bpermute_b32 v40, v169, v24
	ds_bpermute_b32 v45, v169, v29
	ds_bpermute_b32 v41, v169, v25
	ds_bpermute_b32 v42, v169, v30
	ds_bpermute_b32 v38, v169, v26
	ds_bpermute_b32 v43, v169, v31
	ds_bpermute_b32 v39, v169, v27
	s_and_saveexec_b64 s[42:43], s[36:37]
	s_cbranch_execz .LBB0_307
	v_lshl_add_u64 v[58:59], s[20:21], 0, v[32:33]
	global_load_dwordx4 v[46:49], v[58:59], off
	global_load_dwordx4 v[50:53], v[58:59], off offset:32
	global_load_dwordx4 v[54:57], v[58:59], off offset:16
	s_nop 0
	global_load_dwordx4 v[58:61], v[58:59], off offset:48
	s_waitcnt vmcnt(3)
	v_pk_mul_f32 v[30:31], v[30:31], v[48:49]
	v_pk_mul_f32 v[28:29], v[28:29], v[46:47]
	s_waitcnt vmcnt(2) lgkmcnt(5)
	v_pk_mul_f32 v[44:45], v[50:51], v[44:45]
	s_waitcnt lgkmcnt(1)
	v_pk_mul_f32 v[42:43], v[52:53], v[42:43]
	s_waitcnt vmcnt(1)
	v_pk_mul_f32 v[26:27], v[26:27], v[56:57]
	v_pk_mul_f32 v[24:25], v[24:25], v[54:55]
	s_waitcnt vmcnt(0)
	v_pk_mul_f32 v[40:41], v[58:59], v[40:41]
	s_waitcnt lgkmcnt(0)
	v_pk_mul_f32 v[38:39], v[60:61], v[38:39]
	v_pk_fma_f32 v[30:31], v[140:141], v[42:43], v[30:31]
	v_pk_fma_f32 v[28:29], v[138:139], v[44:45], v[28:29]
	v_pk_fma_f32 v[26:27], v[140:141], v[38:39], v[26:27]
	v_pk_fma_f32 v[24:25], v[138:139], v[40:41], v[24:25]

.LBB0_312:
	v_cvt_pk_bf16_f32 v20, v20, v21
	v_cvt_pk_bf16_f32 v21, v22, v23
	v_cvt_pk_bf16_f32 v23, v18, v19
	v_add_u32_e32 v18, 0xb0, v148
	v_ashrrev_i32_e32 v19, 31, v18
	v_cvt_pk_bf16_f32 v22, v16, v17
	v_lshlrev_b64 v[16:17], 6, v[18:19]
	global_store_dwordx4 v[24:25], v[20:23], off offset:256
	s_and_b64 vcc, exec, s[40:41]
	s_nop 0
	v_lshl_add_u64 v[20:21], v[142:143], 0, v[16:17]
	v_mov_b32_e32 v20, v208
	v_mov_b32_e32 v21, v209
	v_mov_b32_e32 v22, v210
	v_mov_b32_e32 v23, v211
	v_mov_b32_e32 v24, v21
	v_mov_b32_e32 v25, v22
	v_mov_b32_e32 v21, v23
	v_pk_add_f32 v[20:21], v[24:25], v[20:21]
	s_nop 0
	v_add_f32_e32 v20, v20, v21
	v_mov_b32_e32 v21, v20
	s_nop 1
	v_permlane16_swap_b32_e32 v20, v21
	s_waitcnt lgkmcnt(0)
	v_add_f32_e32 v20, v20, v21
	v_mov_b32_e32 v21, v20
	s_nop 1
	v_permlane32_swap_b32_e32 v20, v21
	s_waitcnt lgkmcnt(0)
	v_add_f32_e32 v20, v20, v21
	v_fmamk_f32 v20, v20, 0x3a800000, v216
	v_mul_f32_e32 v21, 0x4b800000, v20
	v_cmp_gt_f32_e64 s[42:43], s29, v20
	s_nop 1
	v_cndmask_b32_e64 v20, v20, v21, s[42:43]
	v_rsq_f32_e32 v20, v20
	s_nop 0
	v_mul_f32_e32 v21, 0x45800000, v20
	v_cndmask_b32_e64 v20, v20, v21, s[42:43]
	v_mul_f32_e32 v20, v174, v20
	v_pk_mul_f32 v[14:15], v[14:15], v[20:21] op_sel_hi:[1,0]
	v_pk_mul_f32 v[12:13], v[12:13], v[20:21] op_sel_hi:[1,0]
	v_pk_mul_f32 v[10:11], v[10:11], v[20:21] op_sel_hi:[1,0]
	v_pk_mul_f32 v[8:9], v[8:9], v[20:21] op_sel_hi:[1,0]
	s_cbranch_vccnz .LBB0_316
	ds_bpermute_b32 v28, v169, v12
	ds_bpermute_b32 v24, v169, v8
	ds_bpermute_b32 v29, v169, v13
	ds_bpermute_b32 v25, v169, v9
	ds_bpermute_b32 v26, v169, v14
	ds_bpermute_b32 v22, v169, v10
	ds_bpermute_b32 v27, v169, v15
	ds_bpermute_b32 v23, v169, v11
	s_and_saveexec_b64 s[42:43], s[36:37]
	s_cbranch_execz .LBB0_315
	v_lshl_add_u64 v[42:43], s[20:21], 0, v[16:17]
	global_load_dwordx4 v[30:33], v[42:43], off
	global_load_dwordx4 v[34:37], v[42:43], off offset:32
	global_load_dwordx4 v[38:41], v[42:43], off offset:16
	s_nop 0
	global_load_dwordx4 v[42:45], v[42:43], off offset:48
	s_waitcnt vmcnt(3)
	v_pk_mul_f32 v[14:15], v[14:15], v[32:33]
	v_pk_mul_f32 v[12:13], v[12:13], v[30:31]
	s_waitcnt vmcnt(2) lgkmcnt(5)
	v_pk_mul_f32 v[28:29], v[34:35], v[28:29]
	s_waitcnt lgkmcnt(1)
	v_pk_mul_f32 v[26:27], v[36:37], v[26:27]
	s_waitcnt vmcnt(1)
	v_pk_mul_f32 v[10:11], v[10:11], v[40:41]
	v_pk_mul_f32 v[8:9], v[8:9], v[38:39]
	s_waitcnt vmcnt(0)
	v_pk_mul_f32 v[24:25], v[42:43], v[24:25]
	s_waitcnt lgkmcnt(0)
	v_pk_mul_f32 v[22:23], v[44:45], v[22:23]
	v_pk_fma_f32 v[14:15], v[140:141], v[26:27], v[14:15]
	v_pk_fma_f32 v[12:13], v[138:139], v[28:29], v[12:13]
	v_pk_fma_f32 v[10:11], v[140:141], v[22:23], v[10:11]
	v_pk_fma_f32 v[8:9], v[138:139], v[24:25], v[8:9]
